# job_fold (branch-phase copy): 12 serialized global loads batched before one wait
# baseline (speedup 1.0000x reference)
; __device__ void job_fold(PP p, unsigned char* smem, int job) {
;     ...
;     const float* src = p->w_in + (size_t)layer * DM * NIN + (size_t)k0 * NIN + 2048 + gi * 128;
; #pragma unroll
;     for (int i = 0; i < 4; ++i) { const int idx = tid + i * 512, k = idx >> 5, c4 = idx & 31; *(f32x4*)(wt + k * 128 + c4 * 4) = *(const f32x4*)(src + (size_t)k * NIN + c4 * 4); }
;     const float* ps = p->pool_w + (size_t)(layer * 4 + gi) * 128 * 128;
; #pragma unroll
;     for (int i = 0; i < 8; ++i) { const int idx = tid + i * 512; *(f32x4*)(pl + idx * 4) = *(const f32x4*)(ps + idx * 4); }
;     __syncthreads();
;     const int d = tid & 127, kg = tid >> 7;
;     float acc[16];
; #pragma unroll
;     for (int e = 0; e < 16; ++e) acc[e] = 0.f;
.LBB0_186:
	s_add_i32 s4, s15, 0xffffffb0
	s_add_i32 s6, s4, s47
	v_mov_b32_e32 v8, v160
	s_ashr_i32 s8, s6, 7
	s_load_dwordx2 s[10:11], s[0:1], 0x40
	s_load_dwordx2 s[6:7], s[0:1], 0x58
	s_lshr_b32 s9, s4, 5
	s_lshl_b32 s4, s4, 6
	s_and_b32 s4, s4, 0x7c0
	s_mul_i32 s13, s8, 0x7000000
	s_mul_hi_i32 s12, s8, 0x7000000
	s_waitcnt lgkmcnt(0)
	s_add_u32 s10, s10, s13
	s_addc_u32 s11, s11, s12
	s_mul_i32 s12, s4, 0xe000
	s_add_u32 s12, s10, s12
	s_addc_u32 s13, s11, 0
	s_lshl_b32 s34, s9, 7
	s_lshl_b64 s[10:11], s[34:35], 2
	s_add_u32 s10, s12, s10
	v_lshlrev_b32_e32 v9, 4, v8
	s_addc_u32 s11, s13, s11
	v_and_b32_e32 v162, 0x1f0, v9
	v_lshl_add_u64 v[0:1], s[10:11], 0, v[162:163]
	s_mov_b64 s[10:11], 0x2000
	v_lshl_add_u64 v[6:7], v[0:1], 0, s[10:11]
	v_ashrrev_i32_e32 v10, 5, v8
	v_mad_i64_i32 v[0:1], s[10:11], v10, s29, v[6:7]
	global_load_dwordx4 v[100:103], v[0:1], off
	v_add_u32_e32 v5, 0, v162
	v_lshl_add_u32 v10, v10, 9, v5
	v_lshlrev_b32_e32 v4, 2, v8
	v_and_b32_e32 v69, 0x7f, v8
	v_ashrrev_i32_e32 v68, 7, v8
	v_mov_b32_e32 v64, 0
	v_lshl_add_u32 v70, v68, 13, 0
	v_mov_b32_e32 v65, v64
	v_mov_b32_e32 v32, v64
	v_mov_b32_e32 v33, v64
	v_mov_b32_e32 v56, v64
	v_mov_b32_e32 v57, v64
	v_mov_b32_e32 v24, v64
	v_mov_b32_e32 v25, v64
	v_mov_b32_e32 v48, v64
	v_mov_b32_e32 v49, v64
	v_mov_b32_e32 v16, v64
	v_mov_b32_e32 v17, v64
	v_mov_b32_e32 v40, v64
	v_mov_b32_e32 v41, v64
	v_mov_b32_e32 v148, v10
	v_add_u32_e32 v0, 0x200, v8
	v_ashrrev_i32_e32 v10, 5, v0
	v_mad_i64_i32 v[0:1], s[10:11], v10, s29, v[6:7]
	global_load_dwordx4 v[104:107], v[0:1], off
	v_lshl_add_u32 v10, v10, 9, v5
	v_mov_b32_e32 v149, v10
	v_add_u32_e32 v0, 0x400, v8
	v_ashrrev_i32_e32 v10, 5, v0
	v_mad_i64_i32 v[0:1], s[10:11], v10, s29, v[6:7]
	global_load_dwordx4 v[108:111], v[0:1], off
	v_lshl_add_u32 v10, v10, 9, v5
	v_mov_b32_e32 v150, v10
	v_add_u32_e32 v0, 0x600, v8
	v_ashrrev_i32_e32 v10, 5, v0
	v_mad_i64_i32 v[0:1], s[10:11], v10, s29, v[6:7]
	global_load_dwordx4 v[112:115], v[0:1], off
	s_lshl_b32 s10, s8, 2
	s_add_i32 s10, s10, s9
	s_ashr_i32 s11, s10, 31
	s_lshl_b64 s[10:11], s[10:11], 16
	v_lshl_add_u32 v5, v10, 9, v5
	s_add_u32 s6, s6, s10
	s_addc_u32 s7, s7, s11
	v_mov_b32_e32 v8, v64
	v_mov_b32_e32 v151, v5
	v_ashrrev_i32_e32 v5, 31, v4
	v_lshl_add_u64 v[0:1], v[4:5], 2, s[6:7]
	global_load_dwordx4 v[116:119], v[0:1], off
	v_add_u32_e32 v5, 0, v9
	v_add_u32_e32 v6, 0x8000, v5
	v_mov_b32_e32 v9, v64
	v_mov_b32_e32 v152, v5
	v_add_u32_e32 v0, 0x800, v4
	v_ashrrev_i32_e32 v1, 31, v0
	v_lshl_add_u64 v[0:1], v[0:1], 2, s[6:7]
	global_load_dwordx4 v[120:123], v[0:1], off
	v_mov_b32_e32 v153, v5
	v_add_u32_e32 v0, 0x1000, v4
	v_ashrrev_i32_e32 v1, 31, v0
	v_lshl_add_u64 v[0:1], v[0:1], 2, s[6:7]
	global_load_dwordx4 v[124:127], v[0:1], off
	v_mov_b32_e32 v154, v5
	v_add_u32_e32 v0, 0x1800, v4
	v_ashrrev_i32_e32 v1, 31, v0
	v_lshl_add_u64 v[0:1], v[0:1], 2, s[6:7]
	global_load_dwordx4 v[128:131], v[0:1], off
	v_mov_b32_e32 v155, v5
	v_add_u32_e32 v0, 0x2000, v4
	v_ashrrev_i32_e32 v1, 31, v0
	v_lshl_add_u64 v[0:1], v[0:1], 2, s[6:7]
	global_load_dwordx4 v[132:135], v[0:1], off
	v_mov_b32_e32 v156, v6
	v_add_u32_e32 v0, 0x2800, v4
	v_ashrrev_i32_e32 v1, 31, v0
	v_lshl_add_u64 v[0:1], v[0:1], 2, s[6:7]
	global_load_dwordx4 v[136:139], v[0:1], off
	v_mov_b32_e32 v157, v6
	v_add_u32_e32 v0, 0x3000, v4
	v_ashrrev_i32_e32 v1, 31, v0
	v_lshl_add_u64 v[0:1], v[0:1], 2, s[6:7]
	global_load_dwordx4 v[140:143], v[0:1], off
	v_mov_b32_e32 v158, v6
	v_add_u32_e32 v0, 0x3800, v4
	v_ashrrev_i32_e32 v1, 31, v0
	v_lshl_add_u64 v[0:1], v[0:1], 2, s[6:7]
	global_load_dwordx4 v[144:147], v[0:1], off
	s_add_i32 s6, 0, 0x8000
	v_lshl_add_u32 v71, v69, 2, s6
	s_mov_b32 s6, 0
	v_mov_b32_e32 v159, v6
	s_waitcnt vmcnt(0)
	ds_write_b128 v148, v[100:103]
	ds_write_b128 v149, v[104:107]
	ds_write_b128 v150, v[108:111]
	ds_write_b128 v151, v[112:115]
	ds_write_b128 v152, v[116:119] offset:32768
	ds_write_b128 v153, v[120:123] offset:40960
	ds_write_b128 v154, v[124:127] offset:49152
	ds_write_b128 v155, v[128:131] offset:57344
	ds_write_b128 v156, v[132:135] offset:32768
	ds_write_b128 v157, v[136:139] offset:40960
	ds_write_b128 v158, v[140:143] offset:49152
	ds_write_b128 v159, v[144:147] offset:57344
	s_waitcnt lgkmcnt(0)
	s_barrier
